# compression item epilogue: batched cross-wave LDS reduction reads, early touch of bias and second-layer weight lines
# speedup vs baseline: 1.0159x; 1.0018x over previous
; #define GAS __attribute__((address_space(1)))
; #define LAS __attribute__((address_space(3)))
; #define MFMA32(a, b, c) __builtin_amdgcn_mfma_f32_32x32x16_bf16((a), (b), (c), 0, 0, 0)
; __device__ __forceinline__ void compress_item_mfma(const bf16* PROJ, const bf16* W1T, const bf16* W2T, const float* PW1, bf16* KC, unsigned char* VCB, int it, LAS unsigned char* lds, int wave, int lane) {
;     const int kv = it >> 5, b = (it >> 4) & 1, g = (it >> 3) & 1, ct = it & 7, cl = lane & 31, hh = lane >> 5;
;     const int colbase = (kv ? C_CMPV : C_CMPK) + g * 64, tokbase = 16 * (32 * ct + cl);
;     const bf16* w1t = W1T + (size_t)kv * 64 * 2048 + (size_t)cl * 2048 + 8 * hh;
;     f32x16 hT[2]; zero_ot<2>(hT);
; #pragma unroll 4
;     for (int s = 16 * wave; s < 16 * wave + 16; ++s) { int tok = tokbase + (s >> 2); tok = tok < SEQ ? tok : SEQ - 1;
;         const bf16x8 bfr = *(const GAS bf16x8*)(PROJ + ((size_t)b * SEQ + tok) * NINP + colbase + 16 * (s & 3) + 8 * hh);
;         const bf16x8 a0 = *(const GAS bf16x8*)(w1t + 16 * s), a1 = *(const GAS bf16x8*)(w1t + (size_t)32 * 2048 + 16 * s);
;         hT[0] = MFMA32(a0, bfr, hT[0]); hT[1] = MFMA32(a1, bfr, hT[1]); }
;     LAS float* part = (LAS float*)lds;
; #pragma unroll
;     for (int nt = 0; nt < 2; ++nt)
; #pragma unroll
;         for (int r = 0; r < 16; ++r) part[(wave * 32 + nt * 16 + r) * 64 + lane] = hT[nt][r];
;     __syncthreads();
;     if (wave == 0) {
; #pragma unroll 1
;         for (int w = 1; w < 8; ++w) { const LAS float* pw = part + (size_t)(w * 32) * 64 + lane;
; #pragma unroll
;             for (int nt = 0; nt < 2; ++nt)
; #pragma unroll
;                 for (int r = 0; r < 16; ++r) hT[nt][r] += pw[(nt * 16 + r) * 64]; }
.LBB0_428:
	s_ashr_i32 s13, s12, 2
	v_add_u32_e32 v41, s13, v40
	v_lshl_add_u64 v[66:67], v[38:39], 0, s[20:21]
	s_mov_b32 s13, 0x500000
	v_add_co_u32_e32 v70, vcc, s13, v66
	s_mov_b32 s13, 0x520000
	s_nop 0
	v_addc_co_u32_e32 v71, vcc, 0, v67, vcc
	v_add_co_u32_e32 v72, vcc, s13, v66
	s_nop 1
	v_addc_co_u32_e32 v73, vcc, 0, v67, vcc
	v_min_i32_e32 v41, 0xfff, v41
	v_add_u32_e32 v41, s4, v41
	v_mad_i64_i32 v[46:47], s[30:31], v41, s83, v[36:37]
	global_load_dwordx4 v[146:149], v[70:71], off
	global_load_dwordx4 v[150:153], v[72:73], off
	global_load_dwordx4 v[154:157], v[46:47], off
	global_load_dwordx4 v[158:161], v[70:71], off offset:32
	global_load_dwordx4 v[162:165], v[72:73], off offset:32
	global_load_dwordx4 v[166:169], v[46:47], off offset:32
	global_load_dwordx4 v[170:173], v[70:71], off offset:64
	global_load_dwordx4 v[174:177], v[72:73], off offset:64
	global_load_dwordx4 v[178:181], v[46:47], off offset:64
	global_load_dwordx4 v[182:185], v[70:71], off offset:96
	global_load_dwordx4 v[214:217], v[72:73], off offset:96
	global_load_dwordx4 v[218:221], v[46:47], off offset:96
	s_add_i32 s12, s12, 4
	s_add_u32 s20, s20, 0x80
	s_addc_u32 s21, s21, 0
	s_cmpk_eq_i32 s20, 0x200
	s_waitcnt vmcnt(9)
	v_mfma_f32_32x32x16_bf16 v[20:35], v[146:149], v[154:157], v[20:35]
	v_mfma_f32_32x32x16_bf16 v[4:19], v[150:153], v[154:157], v[4:19]
	s_waitcnt vmcnt(6)
	v_mfma_f32_32x32x16_bf16 v[20:35], v[158:161], v[166:169], v[20:35]
	v_mfma_f32_32x32x16_bf16 v[4:19], v[162:165], v[166:169], v[4:19]
	s_waitcnt vmcnt(3)
	v_mfma_f32_32x32x16_bf16 v[20:35], v[170:173], v[178:181], v[20:35]
	v_mfma_f32_32x32x16_bf16 v[4:19], v[174:177], v[178:181], v[4:19]
	s_waitcnt vmcnt(0)
	v_mfma_f32_32x32x16_bf16 v[20:35], v[182:185], v[218:221], v[20:35]
	v_mfma_f32_32x32x16_bf16 v[4:19], v[214:217], v[218:221], v[4:19]
	s_cbranch_scc0 .LBB0_428
	v_add_u32_e32 v36, s10, v60
	s_andn2_b64 vcc, exec, s[14:15]
	s_nop 6
	ds_write2st64_b32 v36, v20, v21 offset1:1
	ds_write2st64_b32 v36, v22, v23 offset0:2 offset1:3
	ds_write2st64_b32 v36, v24, v25 offset0:4 offset1:5
	ds_write2st64_b32 v36, v26, v27 offset0:6 offset1:7
	ds_write2st64_b32 v36, v28, v29 offset0:8 offset1:9
	ds_write2st64_b32 v36, v30, v31 offset0:10 offset1:11
	ds_write2st64_b32 v36, v32, v33 offset0:12 offset1:13
	ds_write2st64_b32 v36, v34, v35 offset0:14 offset1:15
	ds_write2st64_b32 v36, v4, v5 offset0:16 offset1:17
	ds_write2st64_b32 v36, v6, v7 offset0:18 offset1:19
	ds_write2st64_b32 v36, v8, v9 offset0:20 offset1:21
	ds_write2st64_b32 v36, v10, v11 offset0:22 offset1:23
	ds_write2st64_b32 v36, v12, v13 offset0:24 offset1:25
	ds_write2st64_b32 v36, v14, v15 offset0:26 offset1:27
	ds_write2st64_b32 v36, v16, v17 offset0:28 offset1:29
	ds_write2st64_b32 v36, v18, v19 offset0:30 offset1:31
	s_waitcnt lgkmcnt(0)
	s_barrier
	s_cbranch_vccnz .LBB0_426
	s_movk_i32 s4, 0x2000
	s_lshl_b32 s12, s22, 6
	s_ashr_i32 s13, s12, 31
	v_lshl_add_u64 v[214:215], s[12:13], 2, v[48:49]
	global_load_dwordx4 v[216:219], v[214:215], off
	global_load_dwordx4 v[220:223], v[214:215], off offset:128
	s_lshl_b64 s[12:13], s[22:23], 13
	v_lshl_add_u64 v[224:225], v[50:51], 0, s[12:13]
	s_mov_b64 s[12:13], 0x1000
	global_load_dwordx2 v[226:227], v[224:225], off
	v_lshl_add_u64 v[240:241], v[224:225], 0, s[12:13]
	global_load_dwordx2 v[242:243], v[240:241], off
.LBB0_431:
	v_add_u32_e32 v38, s4, v60
	ds_read2st64_b32 v[146:147], v38 offset1:1
	ds_read2st64_b32 v[148:149], v38 offset0:2 offset1:3
	ds_read2st64_b32 v[150:151], v38 offset0:4 offset1:5
	ds_read2st64_b32 v[152:153], v38 offset0:6 offset1:7
	ds_read2st64_b32 v[154:155], v38 offset0:8 offset1:9
	ds_read2st64_b32 v[156:157], v38 offset0:10 offset1:11
	ds_read2st64_b32 v[158:159], v38 offset0:12 offset1:13
	ds_read2st64_b32 v[160:161], v38 offset0:14 offset1:15
	ds_read2st64_b32 v[162:163], v38 offset0:16 offset1:17
	ds_read2st64_b32 v[164:165], v38 offset0:18 offset1:19
	ds_read2st64_b32 v[166:167], v38 offset0:20 offset1:21
	ds_read2st64_b32 v[168:169], v38 offset0:22 offset1:23
	ds_read2st64_b32 v[170:171], v38 offset0:24 offset1:25
	ds_read2st64_b32 v[172:173], v38 offset0:26 offset1:27
	ds_read2st64_b32 v[174:175], v38 offset0:28 offset1:29
	ds_read2st64_b32 v[176:177], v38 offset0:30 offset1:31
	s_addk_i32 s4, 0x2000
	s_cmp_eq_u32 s4, 0x10000
	s_waitcnt lgkmcnt(8)
	v_pk_add_f32 v[20:21], v[20:21], v[146:147]
	v_pk_add_f32 v[22:23], v[22:23], v[148:149]
	v_pk_add_f32 v[24:25], v[24:25], v[150:151]
	v_pk_add_f32 v[26:27], v[26:27], v[152:153]
	v_pk_add_f32 v[28:29], v[28:29], v[154:155]
	v_pk_add_f32 v[30:31], v[30:31], v[156:157]
	v_pk_add_f32 v[32:33], v[32:33], v[158:159]
	v_pk_add_f32 v[34:35], v[34:35], v[160:161]
	s_waitcnt lgkmcnt(0)
	v_pk_add_f32 v[4:5], v[4:5], v[162:163]
	v_pk_add_f32 v[6:7], v[6:7], v[164:165]
	v_pk_add_f32 v[8:9], v[8:9], v[166:167]
	v_pk_add_f32 v[10:11], v[10:11], v[168:169]
	v_pk_add_f32 v[12:13], v[12:13], v[170:171]
	v_pk_add_f32 v[14:15], v[14:15], v[172:173]
	v_pk_add_f32 v[16:17], v[16:17], v[174:175]
	v_pk_add_f32 v[18:19], v[18:19], v[176:177]
	s_cbranch_scc0 .LBB0_431
; __device__ __forceinline__ float gelu_tanh(float x) { const float u = 0.7978845608028654f * (x + 0.044715f * x * x * x); return x * __builtin_amdgcn_rcpf(1.f + __builtin_amdgcn_exp2f(-2.885390081777927f * u)); }
; __device__ __forceinline__ unsigned cvtpk(float lo, float hi) { f32x2_t v = {lo, hi}; bf16x2_t b = __builtin_convertvector(v, bf16x2_t); return __builtin_bit_cast(unsigned, b); }
; __device__ __forceinline__ void compress_item_mfma(const bf16* PROJ, const bf16* W1T, const bf16* W2T, const float* PW1, bf16* KC, unsigned char* VCB, int it, LAS unsigned char* lds, int wave, int lane) {
;     ...
;         for (int nt = 0; nt < 2; ++nt) {
; #pragma unroll
;             for (int g4 = 0; g4 < 4; ++g4) { const f32x4 pb = *(const f32x4*)(PW1 + kv * 64 + 32 * nt + 8 * g4 + 4 * hh);
;                 hT[nt][4 * g4] = gelu_tanh(hT[nt][4 * g4] + pb.x); hT[nt][4 * g4 + 1] = gelu_tanh(hT[nt][4 * g4 + 1] + pb.y); hT[nt][4 * g4 + 2] = gelu_tanh(hT[nt][4 * g4 + 2] + pb.z); hT[nt][4 * g4 + 3] = gelu_tanh(hT[nt][4 * g4 + 3] + pb.w); }
; #pragma unroll
;             for (int s2 = 0; s2 < 2; ++s2) { v4u p; p.x = cvtpk(hT[nt][8 * s2], hT[nt][8 * s2 + 1]); p.y = cvtpk(hT[nt][8 * s2 + 2], hT[nt][8 * s2 + 3]); p.z = cvtpk(hT[nt][8 * s2 + 4], hT[nt][8 * s2 + 5]); p.w = cvtpk(hT[nt][8 * s2 + 6], hT[nt][8 * s2 + 7]);
;                 xf[nt][s2] = __builtin_bit_cast(bf16x8, p); } }
	s_lshl_b32 s12, s22, 6
	s_ashr_i32 s13, s12, 31
	v_lshl_add_u64 v[40:41], s[12:13], 2, v[48:49]
	flat_load_dwordx4 v[36:39], v[40:41]
	s_lshl_b64 s[12:13], s[22:23], 13
	s_movk_i32 s4, 0x1000
	s_mov_b64 s[20:21], -1
	s_waitcnt vmcnt(0) lgkmcnt(0)
	v_pk_add_f32 v[20:21], v[20:21], v[36:37]
	s_nop 0
	v_mul_f32_e32 v36, 0x3d372713, v20
	v_mul_f32_e32 v37, 0x3d372713, v21
	v_mul_f32_e32 v36, v20, v36
	v_mul_f32_e32 v37, v21, v37
	v_fma_f32 v36, v20, v36, v20
	v_fma_f32 v37, v21, v37, v21
	v_mul_f32_e32 v36, 0x3f4c422a, v36
	v_mul_f32_e32 v37, 0x3f4c422a, v37
	v_mul_f32_e32 v36, 0xc038aa3b, v36
	v_mul_f32_e32 v37, 0xc038aa3b, v37
	v_exp_f32_e32 v36, v36
	v_exp_f32_e32 v37, v37
	v_pk_add_f32 v[22:23], v[22:23], v[38:39]
	v_add_f32_e32 v36, 1.0, v36
	v_add_f32_e32 v37, 1.0, v37
	v_rcp_f32_e32 v36, v36
	v_rcp_f32_e32 v37, v37
	s_nop 0
	v_pk_mul_f32 v[20:21], v[20:21], v[36:37]
	v_mul_f32_e32 v36, 0x3d372713, v22
	v_mul_f32_e32 v37, 0x3d372713, v23
	v_mul_f32_e32 v36, v22, v36
	v_mul_f32_e32 v37, v23, v37
	v_fma_f32 v36, v22, v36, v22
	v_fma_f32 v37, v23, v37, v23
	v_mul_f32_e32 v36, 0x3f4c422a, v36
	v_mul_f32_e32 v37, 0x3f4c422a, v37
	v_mul_f32_e32 v36, 0xc038aa3b, v36
	v_mul_f32_e32 v37, 0xc038aa3b, v37
	v_exp_f32_e32 v36, v36
	v_exp_f32_e32 v37, v37
	v_cvt_pk_bf16_f32 v20, v20, v21
	v_add_f32_e32 v36, 1.0, v36
	v_add_f32_e32 v37, 1.0, v37
	v_rcp_f32_e32 v36, v36
	v_rcp_f32_e32 v37, v37
	s_nop 0
	v_pk_mul_f32 v[22:23], v[22:23], v[36:37]
	flat_load_dwordx4 v[36:39], v[40:41] offset:32
	v_cvt_pk_bf16_f32 v21, v22, v23
	s_waitcnt vmcnt(0) lgkmcnt(0)
	v_pk_add_f32 v[24:25], v[24:25], v[36:37]
	s_nop 0
	v_mul_f32_e32 v36, 0x3d372713, v24
	v_mul_f32_e32 v37, 0x3d372713, v25
	v_mul_f32_e32 v36, v24, v36
	v_mul_f32_e32 v37, v25, v37
	v_fma_f32 v36, v24, v36, v24
	v_fma_f32 v37, v25, v37, v25
	v_mul_f32_e32 v36, 0x3f4c422a, v36
	v_mul_f32_e32 v37, 0x3f4c422a, v37
	v_mul_f32_e32 v36, 0xc038aa3b, v36
	v_mul_f32_e32 v37, 0xc038aa3b, v37
	v_exp_f32_e32 v36, v36
	v_exp_f32_e32 v37, v37
	v_pk_add_f32 v[26:27], v[26:27], v[38:39]
	v_add_f32_e32 v36, 1.0, v36
	v_add_f32_e32 v37, 1.0, v37
	v_rcp_f32_e32 v36, v36
	v_rcp_f32_e32 v37, v37
	s_nop 0
	v_pk_mul_f32 v[24:25], v[24:25], v[36:37]
	v_mul_f32_e32 v36, 0x3d372713, v26
	v_mul_f32_e32 v37, 0x3d372713, v27
	v_mul_f32_e32 v36, v26, v36
	v_mul_f32_e32 v37, v27, v37
	v_fma_f32 v36, v26, v36, v26
	v_fma_f32 v37, v27, v37, v27
	v_mul_f32_e32 v36, 0x3f4c422a, v36
	v_mul_f32_e32 v37, 0x3f4c422a, v37
	v_mul_f32_e32 v36, 0xc038aa3b, v36
	v_mul_f32_e32 v37, 0xc038aa3b, v37
	v_exp_f32_e32 v36, v36
	v_exp_f32_e32 v37, v37
	v_cvt_pk_bf16_f32 v22, v24, v25
	v_add_f32_e32 v36, 1.0, v36
	v_add_f32_e32 v37, 1.0, v37
	v_rcp_f32_e32 v36, v36
	v_rcp_f32_e32 v37, v37
	s_nop 0
	v_pk_mul_f32 v[26:27], v[26:27], v[36:37]
	flat_load_dwordx4 v[36:39], v[40:41] offset:64
	v_cvt_pk_bf16_f32 v23, v26, v27
	flat_load_dwordx4 v[24:27], v[40:41] offset:128
	s_waitcnt vmcnt(0) lgkmcnt(0)
	v_pk_add_f32 v[28:29], v[28:29], v[36:37]
	s_nop 0
	v_mul_f32_e32 v36, 0x3d372713, v28
	v_mul_f32_e32 v37, 0x3d372713, v29
	v_pk_add_f32 v[4:5], v[4:5], v[24:25]
	v_mul_f32_e32 v36, v28, v36
	v_mul_f32_e32 v37, v29, v37
	v_mul_f32_e32 v24, 0x3d372713, v4
	v_mul_f32_e32 v25, 0x3d372713, v5
	v_fma_f32 v36, v28, v36, v28
	v_fma_f32 v37, v29, v37, v29
	v_mul_f32_e32 v24, v4, v24
	v_mul_f32_e32 v25, v5, v25
	v_mul_f32_e32 v36, 0x3f4c422a, v36
	v_mul_f32_e32 v37, 0x3f4c422a, v37
	v_fma_f32 v24, v4, v24, v4
	v_fma_f32 v25, v5, v25, v5
	v_mul_f32_e32 v36, 0xc038aa3b, v36
	v_mul_f32_e32 v37, 0xc038aa3b, v37
	v_mul_f32_e32 v24, 0x3f4c422a, v24
	v_mul_f32_e32 v25, 0x3f4c422a, v25
	v_exp_f32_e32 v36, v36
	v_exp_f32_e32 v37, v37
	v_mul_f32_e32 v24, 0xc038aa3b, v24
	v_mul_f32_e32 v25, 0xc038aa3b, v25
	v_exp_f32_e32 v24, v24
	v_exp_f32_e32 v25, v25
	v_add_f32_e32 v36, 1.0, v36
	v_add_f32_e32 v37, 1.0, v37
	v_rcp_f32_e32 v36, v36
	v_rcp_f32_e32 v37, v37
	v_add_f32_e32 v24, 1.0, v24
	v_add_f32_e32 v25, 1.0, v25
	v_rcp_f32_e32 v24, v24
	v_rcp_f32_e32 v25, v25
	v_pk_mul_f32 v[36:37], v[28:29], v[36:37]
	v_pk_add_f32 v[28:29], v[30:31], v[38:39]
	v_pk_add_f32 v[6:7], v[6:7], v[26:27]
	v_mul_f32_e32 v30, 0x3d372713, v28
	v_mul_f32_e32 v31, 0x3d372713, v29
	v_pk_mul_f32 v[4:5], v[4:5], v[24:25]
	v_mul_f32_e32 v24, 0x3d372713, v6
	v_mul_f32_e32 v25, 0x3d372713, v7
	v_mul_f32_e32 v30, v28, v30
	v_mul_f32_e32 v31, v29, v31
	v_mul_f32_e32 v24, v6, v24
	v_mul_f32_e32 v25, v7, v25
	v_fma_f32 v30, v28, v30, v28
	v_fma_f32 v31, v29, v31, v29
	v_fma_f32 v24, v6, v24, v6
	v_fma_f32 v25, v7, v25, v7
	v_mul_f32_e32 v30, 0x3f4c422a, v30
	v_mul_f32_e32 v31, 0x3f4c422a, v31
	v_mul_f32_e32 v24, 0x3f4c422a, v24
	v_mul_f32_e32 v25, 0x3f4c422a, v25
	v_mul_f32_e32 v30, 0xc038aa3b, v30
	v_mul_f32_e32 v31, 0xc038aa3b, v31
	v_mul_f32_e32 v24, 0xc038aa3b, v24
	v_mul_f32_e32 v25, 0xc038aa3b, v25
	v_exp_f32_e32 v30, v30
	v_exp_f32_e32 v31, v31
	v_exp_f32_e32 v24, v24
	v_exp_f32_e32 v25, v25
	v_add_f32_e32 v30, 1.0, v30
	v_add_f32_e32 v31, 1.0, v31
	v_add_f32_e32 v24, 1.0, v24
	v_add_f32_e32 v25, 1.0, v25
	v_rcp_f32_e32 v30, v30
	v_rcp_f32_e32 v31, v31
	v_rcp_f32_e32 v24, v24
	v_rcp_f32_e32 v25, v25
	v_cvt_pk_bf16_f32 v44, v4, v5
	v_pk_mul_f32 v[38:39], v[28:29], v[30:31]
	flat_load_dwordx4 v[28:31], v[40:41] offset:96
	v_pk_mul_f32 v[6:7], v[6:7], v[24:25]
	flat_load_dwordx4 v[24:27], v[40:41] offset:160
	v_cvt_pk_bf16_f32 v45, v6, v7
	v_cvt_pk_bf16_f32 v36, v36, v37
	v_cvt_pk_bf16_f32 v37, v38, v39
	s_waitcnt vmcnt(0) lgkmcnt(0)
; __device__ __forceinline__ float gelu_tanh(float x) { const float u = 0.7978845608028654f * (x + 0.044715f * x * x * x); return x * __builtin_amdgcn_rcpf(1.f + __builtin_amdgcn_exp2f(-2.885390081777927f * u)); }
; __device__ __forceinline__ unsigned cvtpk(float lo, float hi) { f32x2_t v = {lo, hi}; bf16x2_t b = __builtin_convertvector(v, bf16x2_t); return __builtin_bit_cast(unsigned, b); }
; #define MFMA32(a, b, c) __builtin_amdgcn_mfma_f32_32x32x16_bf16((a), (b), (c), 0, 0, 0)
; __device__ __forceinline__ void compress_item_mfma(const bf16* PROJ, const bf16* W1T, const bf16* W2T, const float* PW1, bf16* KC, unsigned char* VCB, int it, LAS unsigned char* lds, int wave, int lane) {
;     ...
;             for (int g4 = 0; g4 < 4; ++g4) { const f32x4 pb = *(const f32x4*)(PW1 + kv * 64 + 32 * nt + 8 * g4 + 4 * hh);
;                 hT[nt][4 * g4] = gelu_tanh(hT[nt][4 * g4] + pb.x); hT[nt][4 * g4 + 1] = gelu_tanh(hT[nt][4 * g4 + 1] + pb.y); hT[nt][4 * g4 + 2] = gelu_tanh(hT[nt][4 * g4 + 2] + pb.z); hT[nt][4 * g4 + 3] = gelu_tanh(hT[nt][4 * g4 + 3] + pb.w); }
; #pragma unroll
;             for (int s2 = 0; s2 < 2; ++s2) { v4u p; p.x = cvtpk(hT[nt][8 * s2], hT[nt][8 * s2 + 1]); p.y = cvtpk(hT[nt][8 * s2 + 2], hT[nt][8 * s2 + 3]); p.z = cvtpk(hT[nt][8 * s2 + 4], hT[nt][8 * s2 + 5]); p.w = cvtpk(hT[nt][8 * s2 + 6], hT[nt][8 * s2 + 7]);
;                 xf[nt][s2] = __builtin_bit_cast(bf16x8, p); } }
;         f32x16 oT[2]; zero_ot<2>(oT);
; #pragma unroll
;         for (int n2t = 0; n2t < 2; ++n2t)
; #pragma unroll
;             for (int nt = 0; nt < 2; ++nt)
; #pragma unroll
;                 for (int s2 = 0; s2 < 2; ++s2) { const bf16* wp = W2T + (size_t)kv * 64 * 64 + (size_t)(32 * n2t + cl) * 64 + 32 * nt + 16 * s2 + 4 * hh;
;                     const v2u lo = *(const v2u*)wp, hi = *(const v2u*)(wp + 8); v4u a; a.x = lo.x; a.y = lo.y; a.z = hi.x; a.w = hi.y;
;                     oT[n2t] = MFMA32(__builtin_bit_cast(bf16x8, a), xf[nt][s2], oT[n2t]); }
	v_pk_add_f32 v[28:29], v[32:33], v[28:29]
	s_nop 0
	v_mul_f32_e32 v32, 0x3d372713, v28
	v_pk_add_f32 v[8:9], v[8:9], v[24:25]
	v_pk_add_f32 v[10:11], v[10:11], v[26:27]
	v_mul_f32_e32 v24, 0x3d372713, v8
	v_mul_f32_e32 v25, 0x3d372713, v9
	v_mul_f32_e32 v24, v8, v24
	v_mul_f32_e32 v25, v9, v25
	v_fma_f32 v24, v8, v24, v8
	v_fma_f32 v25, v9, v25, v9
	v_mul_f32_e32 v24, 0x3f4c422a, v24
	v_mul_f32_e32 v25, 0x3f4c422a, v25
	v_mul_f32_e32 v24, 0xc038aa3b, v24
	v_mul_f32_e32 v25, 0xc038aa3b, v25
	v_exp_f32_e32 v24, v24
	v_exp_f32_e32 v25, v25
	v_mul_f32_e32 v33, 0x3d372713, v29
	v_mul_f32_e32 v32, v28, v32
	v_add_f32_e32 v24, 1.0, v24
	v_add_f32_e32 v25, 1.0, v25
	v_rcp_f32_e32 v24, v24
	v_rcp_f32_e32 v25, v25
	v_mul_f32_e32 v33, v29, v33
	v_fma_f32 v32, v28, v32, v28
	v_fma_f32 v33, v29, v33, v29
	v_pk_mul_f32 v[8:9], v[8:9], v[24:25]
	v_mul_f32_e32 v24, 0x3d372713, v10
	v_mul_f32_e32 v25, 0x3d372713, v11
	v_mul_f32_e32 v24, v10, v24
	v_mul_f32_e32 v25, v11, v25
	v_fma_f32 v24, v10, v24, v10
	v_fma_f32 v25, v11, v25, v11
	v_mul_f32_e32 v24, 0x3f4c422a, v24
	v_mul_f32_e32 v25, 0x3f4c422a, v25
	v_mul_f32_e32 v24, 0xc038aa3b, v24
	v_mul_f32_e32 v25, 0xc038aa3b, v25
	v_exp_f32_e32 v24, v24
	v_exp_f32_e32 v25, v25
	v_mul_f32_e32 v32, 0x3f4c422a, v32
	v_mul_f32_e32 v33, 0x3f4c422a, v33
	v_add_f32_e32 v24, 1.0, v24
	v_add_f32_e32 v25, 1.0, v25
	v_rcp_f32_e32 v24, v24
	v_rcp_f32_e32 v25, v25
	v_mul_f32_e32 v32, 0xc038aa3b, v32
	v_mul_f32_e32 v33, 0xc038aa3b, v33
	v_exp_f32_e32 v32, v32
	v_pk_mul_f32 v[10:11], v[10:11], v[24:25]
	flat_load_dwordx4 v[24:27], v[40:41] offset:192
	v_exp_f32_e32 v33, v33
	v_add_f32_e32 v32, 1.0, v32
	v_rcp_f32_e32 v32, v32
	v_pk_add_f32 v[30:31], v[34:35], v[30:31]
	v_add_f32_e32 v33, 1.0, v33
	v_rcp_f32_e32 v33, v33
	v_cvt_pk_bf16_f32 v46, v8, v9
	v_cvt_pk_bf16_f32 v47, v10, v11
	v_pk_mul_f32 v[28:29], v[28:29], v[32:33]
	s_nop 0
	v_cvt_pk_bf16_f32 v38, v28, v29
	v_mul_f32_e32 v32, 0x3d372713, v30
	v_mul_f32_e32 v33, 0x3d372713, v31
	v_mul_f32_e32 v32, v30, v32
	v_mul_f32_e32 v33, v31, v33
	v_fma_f32 v32, v30, v32, v30
	v_fma_f32 v33, v31, v33, v31
	v_mul_f32_e32 v32, 0x3f4c422a, v32
	v_mul_f32_e32 v33, 0x3f4c422a, v33
	v_mul_f32_e32 v32, 0xc038aa3b, v32
	v_mul_f32_e32 v33, 0xc038aa3b, v33
	v_exp_f32_e32 v32, v32
	v_exp_f32_e32 v33, v33
	v_add_f32_e32 v32, 1.0, v32
	v_add_f32_e32 v33, 1.0, v33
	v_rcp_f32_e32 v32, v32
	v_rcp_f32_e32 v33, v33
	s_waitcnt vmcnt(0) lgkmcnt(0)
	v_pk_add_f32 v[12:13], v[12:13], v[24:25]
	s_nop 0
	v_mul_f32_e32 v24, 0x3d372713, v12
	v_mul_f32_e32 v25, 0x3d372713, v13
	v_mul_f32_e32 v24, v12, v24
	v_mul_f32_e32 v25, v13, v25
	v_fma_f32 v24, v12, v24, v12
	v_fma_f32 v25, v13, v25, v13
	v_mul_f32_e32 v24, 0x3f4c422a, v24
	v_mul_f32_e32 v25, 0x3f4c422a, v25
	v_mul_f32_e32 v24, 0xc038aa3b, v24
	v_mul_f32_e32 v25, 0xc038aa3b, v25
	v_exp_f32_e32 v24, v24
	v_exp_f32_e32 v25, v25
	v_pk_add_f32 v[14:15], v[14:15], v[26:27]
	v_pk_mul_f32 v[30:31], v[30:31], v[32:33]
	v_add_f32_e32 v24, 1.0, v24
	v_add_f32_e32 v25, 1.0, v25
	v_rcp_f32_e32 v24, v24
	v_rcp_f32_e32 v25, v25
	v_cvt_pk_bf16_f32 v39, v30, v31
	v_pk_mul_f32 v[12:13], v[12:13], v[24:25]
	v_mul_f32_e32 v24, 0x3d372713, v14
	v_mul_f32_e32 v25, 0x3d372713, v15
	v_mul_f32_e32 v24, v14, v24
	v_mul_f32_e32 v25, v15, v25
	v_fma_f32 v24, v14, v24, v14
	v_fma_f32 v25, v15, v25, v15
	v_mul_f32_e32 v24, 0x3f4c422a, v24
	v_mul_f32_e32 v25, 0x3f4c422a, v25
	v_mul_f32_e32 v24, 0xc038aa3b, v24
	v_mul_f32_e32 v25, 0xc038aa3b, v25
	v_exp_f32_e32 v24, v24
	v_exp_f32_e32 v25, v25
	v_add_f32_e32 v24, 1.0, v24
	v_add_f32_e32 v25, 1.0, v25
	v_rcp_f32_e32 v24, v24
	v_rcp_f32_e32 v25, v25
	s_nop 0
	v_pk_mul_f32 v[14:15], v[14:15], v[24:25]
	flat_load_dwordx4 v[24:27], v[40:41] offset:224
	v_cvt_pk_bf16_f32 v40, v12, v13
	v_cvt_pk_bf16_f32 v41, v14, v15
	s_waitcnt vmcnt(0) lgkmcnt(0)
	v_pk_add_f32 v[16:17], v[16:17], v[24:25]
	s_nop 0
	v_mul_f32_e32 v24, 0x3d372713, v16
	v_mul_f32_e32 v25, 0x3d372713, v17
	v_mul_f32_e32 v24, v16, v24
	v_mul_f32_e32 v25, v17, v25
	v_fma_f32 v24, v16, v24, v16
	v_fma_f32 v25, v17, v25, v17
	v_mul_f32_e32 v24, 0x3f4c422a, v24
	v_mul_f32_e32 v25, 0x3f4c422a, v25
	v_mul_f32_e32 v24, 0xc038aa3b, v24
	v_mul_f32_e32 v25, 0xc038aa3b, v25
	v_exp_f32_e32 v24, v24
	v_exp_f32_e32 v25, v25
	v_pk_add_f32 v[18:19], v[18:19], v[26:27]
	v_add_f32_e32 v24, 1.0, v24
	v_add_f32_e32 v25, 1.0, v25
	v_rcp_f32_e32 v24, v24
	v_rcp_f32_e32 v25, v25
	s_nop 0
	v_pk_mul_f32 v[16:17], v[16:17], v[24:25]
	v_mul_f32_e32 v24, 0x3d372713, v18
	v_mul_f32_e32 v25, 0x3d372713, v19
	v_mul_f32_e32 v24, v18, v24
	v_mul_f32_e32 v25, v19, v25
	v_fma_f32 v24, v18, v24, v18
	v_fma_f32 v25, v19, v25, v19
	v_mul_f32_e32 v24, 0x3f4c422a, v24
	v_mul_f32_e32 v25, 0x3f4c422a, v25
	v_mul_f32_e32 v24, 0xc038aa3b, v24
	v_mul_f32_e32 v25, 0xc038aa3b, v25
	v_exp_f32_e32 v24, v24
	v_exp_f32_e32 v25, v25
	v_cvt_pk_bf16_f32 v42, v16, v17
	v_add_f32_e32 v24, 1.0, v24
	v_add_f32_e32 v25, 1.0, v25
	v_rcp_f32_e32 v24, v24
	v_rcp_f32_e32 v25, v25
	s_nop 0
	v_pk_mul_f32 v[18:19], v[18:19], v[24:25]
	v_lshl_add_u64 v[24:25], v[50:51], 0, s[12:13]
	flat_load_dwordx2 v[4:5], v[24:25]
	flat_load_dwordx2 v[6:7], v[24:25] offset:16
	flat_load_dwordx2 v[26:27], v[24:25] offset:32
	flat_load_dwordx2 v[28:29], v[24:25] offset:48
	v_cvt_pk_bf16_f32 v43, v18, v19
	s_waitcnt vmcnt(0) lgkmcnt(0)
	v_mfma_f32_32x32x16_bf16 v[4:19], v[4:7], v[20:23], 0
	v_add_co_u32_e32 v66, vcc, s4, v24
	s_nop 1
	v_addc_co_u32_e32 v67, vcc, 0, v25, vcc
	s_and_b64 vcc, exec, s[16:17]
	v_mfma_f32_32x32x16_bf16 v[4:19], v[26:29], v[36:39], v[4:19]
	flat_load_dwordx2 v[26:27], v[24:25] offset:64
	flat_load_dwordx2 v[28:29], v[24:25] offset:80
	s_waitcnt vmcnt(0) lgkmcnt(0)
	v_mfma_f32_32x32x16_bf16 v[4:19], v[26:29], v[44:47], v[4:19]
	flat_load_dwordx2 v[26:27], v[24:25] offset:96
	flat_load_dwordx2 v[28:29], v[24:25] offset:112
	s_waitcnt vmcnt(0) lgkmcnt(0)
	v_mfma_f32_32x32x16_bf16 v[4:19], v[26:29], v[40:43], v[4:19]
	flat_load_dwordx2 v[24:25], v[66:67]
	flat_load_dwordx2 v[26:27], v[66:67] offset:16
	flat_load_dwordx2 v[62:63], v[66:67] offset:32
	flat_load_dwordx2 v[64:65], v[66:67] offset:48
	s_waitcnt vmcnt(0) lgkmcnt(0)
	v_mfma_f32_32x32x16_bf16 v[20:35], v[24:27], v[20:23], 0
	v_mfma_f32_32x32x16_bf16 v[20:35], v[62:65], v[36:39], v[20:35]
	flat_load_dwordx2 v[36:37], v[66:67] offset:64
	flat_load_dwordx2 v[38:39], v[66:67] offset:80
	s_waitcnt vmcnt(0) lgkmcnt(0)
	v_mfma_f32_32x32x16_bf16 v[20:35], v[36:39], v[44:47], v[20:35]
	flat_load_dwordx2 v[36:37], v[66:67] offset:96
	flat_load_dwordx2 v[38:39], v[66:67] offset:112
	s_waitcnt vmcnt(0) lgkmcnt(0)
	v_mfma_f32_32x32x16_bf16 v[20:35], v[36:39], v[40:43], v[20:35]
	s_cbranch_vccz .LBB0_434
; __device__ __forceinline__ unsigned cvtpk(float lo, float hi) { f32x2_t v = {lo, hi}; bf16x2_t b = __builtin_convertvector(v, bf16x2_t); return __builtin_bit_cast(unsigned, b); }
; __device__ __forceinline__ void compress_item_mfma(const bf16* PROJ, const bf16* W1T, const bf16* W2T, const float* PW1, bf16* KC, unsigned char* VCB, int it, LAS unsigned char* lds, int wave, int lane) {
;     ...
;         else { bf16* vb = (bf16*)(VCB + (size_t)((b * 2 + g) * 8 + ct) * 4096) + vtb_pos_of_key(cl);
; #pragma unroll
;             for (int n2t = 0; n2t < 2; ++n2t)
; #pragma unroll
;                 for (int r = 0; r < 16; ++r) vb[n2t * 1024 + ((r & 3) + 8 * (r >> 2) + 4 * hh) * 32] = (bf16)(cvtpk(oT[n2t][r], 0.f) & 0xffffu); }
	s_lshl_b32 s4, s39, 4
	s_lshl_b32 s12, s37, 3
	s_or_b32 s4, s4, s12
	s_or_b32 s4, s4, s18
	s_lshl_b32 s18, s4, 12
	v_cvt_pk_bf16_f32 v38, v4, s0
	v_lshl_add_u64 v[36:37], v[52:53], 0, s[18:19]
	flat_store_short v[36:37], v38
	v_cvt_pk_bf16_f32 v38, v5, s0
	flat_store_short v[36:37], v38 offset:64
	v_cvt_pk_bf16_f32 v38, v6, s0
	flat_store_short v[36:37], v38 offset:128
	v_cvt_pk_bf16_f32 v38, v7, s0
	flat_store_short v[36:37], v38 offset:192
	v_cvt_pk_bf16_f32 v38, v8, s0
	flat_store_short v[36:37], v38 offset:512
	v_cvt_pk_bf16_f32 v38, v9, s0
	flat_store_short v[36:37], v38 offset:576
	v_cvt_pk_bf16_f32 v38, v10, s0
	flat_store_short v[36:37], v38 offset:640
	v_cvt_pk_bf16_f32 v38, v11, s0
	flat_store_short v[36:37], v38 offset:704
	v_cvt_pk_bf16_f32 v38, v12, s0
	flat_store_short v[36:37], v38 offset:1024
	v_cvt_pk_bf16_f32 v38, v13, s0
	flat_store_short v[36:37], v38 offset:1088
	v_cvt_pk_bf16_f32 v38, v14, s0
	flat_store_short v[36:37], v38 offset:1152
	v_cvt_pk_bf16_f32 v38, v15, s0
	flat_store_short v[36:37], v38 offset:1216
	v_cvt_pk_bf16_f32 v38, v16, s0
	flat_store_short v[36:37], v38 offset:1536
	v_cvt_pk_bf16_f32 v38, v17, s0
	flat_store_short v[36:37], v38 offset:1600
	v_cvt_pk_bf16_f32 v38, v18, s0
	flat_store_short v[36:37], v38 offset:1664
	v_cvt_pk_bf16_f32 v38, v19, s0
	flat_store_short v[36:37], v38 offset:1728
	v_cvt_pk_bf16_f32 v38, v20, s0
	flat_store_short v[36:37], v38 offset:2048
	v_cvt_pk_bf16_f32 v38, v21, s0
	flat_store_short v[36:37], v38 offset:2112
	v_cvt_pk_bf16_f32 v38, v22, s0
	flat_store_short v[36:37], v38 offset:2176
	v_cvt_pk_bf16_f32 v38, v23, s0
	flat_store_short v[36:37], v38 offset:2240
	v_cvt_pk_bf16_f32 v38, v24, s0
	flat_store_short v[36:37], v38 offset:2560
	v_cvt_pk_bf16_f32 v38, v25, s0
	flat_store_short v[36:37], v38 offset:2624
	v_cvt_pk_bf16_f32 v38, v26, s0
	flat_store_short v[36:37], v38 offset:2688
	v_cvt_pk_bf16_f32 v38, v27, s0
	flat_store_short v[36:37], v38 offset:2752
	v_cvt_pk_bf16_f32 v38, v28, s0
	flat_store_short v[36:37], v38 offset:3072
	v_cvt_pk_bf16_f32 v38, v29, s0
	flat_store_short v[36:37], v38 offset:3136
	v_cvt_pk_bf16_f32 v38, v30, s0
	flat_store_short v[36:37], v38 offset:3200
	v_cvt_pk_bf16_f32 v38, v31, s0
	flat_store_short v[36:37], v38 offset:3264
	v_cvt_pk_bf16_f32 v38, v32, s0
	flat_store_short v[36:37], v38 offset:3584
	v_cvt_pk_bf16_f32 v38, v33, s0
	flat_store_short v[36:37], v38 offset:3648
	v_cvt_pk_bf16_f32 v38, v34, s0
	flat_store_short v[36:37], v38 offset:3712
	v_cvt_pk_bf16_f32 v38, v35, s0
	flat_store_short v[36:37], v38 offset:3776
	s_mov_b64 s[20:21], 0
